# LayerNorm sample rows: alpha*residual + split-K partial loads issued 16 at a time (one drain per 4 partials) instead of one round trip per load; same summation order
# speedup vs baseline: 1.0186x; 1.0186x over previous
; __device__ __forceinline__ void ln_phase(const float* XF, float* dst, bf16_t* XB, const float* g, const float* bt, const float* srcs, const float* PART, int npart, bool wf32, int gw, int ngw, int lane) {
;     ...
;     for (int m0 = gw; m0 < MT; m0 += 2 * ngw) {
;         f32x4 v[2][4];
; #pragma unroll
;         for (int h = 0; h < 2; ++h) {
;             const int m = m0 + h * ngw; const int mc = m < MT ? m : m0;
;             const u32x2* xr = (const u32x2*)((const bf16_t*)XF + (size_t)(mc < MP ? mc : 0) * DM) + lane;
; #pragma unroll
;             for (int q = 0; q < 4; ++q) { const u32x2 w = xr[64 * q]; v[h][q] = (f32x4){__uint_as_float(w.x << 16), __uint_as_float(w.x & 0xffff0000u), __uint_as_float(w.y << 16), __uint_as_float(w.y & 0xffff0000u)}; }
;         }
.LBB0_515:
	s_add_i32 s8, s66, s90
	s_add_i32 s10, s90, 0x8000
	s_add_i32 s9, s8, 0x8000
	s_cmp_lt_i32 s9, 0x8100
	s_cselect_b32 s6, s9, s10
	s_cmp_lt_i32 s6, 0x8000
	s_cselect_b32 s6, s6, 0
	s_ashr_i32 s7, s6, 31
	s_lshl_b64 s[6:7], s[6:7], 11
	s_cmp_lt_i32 s10, 0x8000
	v_lshl_add_u64 v[32:33], v[36:37], 0, s[6:7]
	s_cselect_b64 s[6:7], -1, 0
	s_and_b64 vcc, s[6:7], exec
	s_cselect_b32 s6, s10, 0
	s_ashr_i32 s7, s6, 31
	s_lshl_b64 s[6:7], s[6:7], 11
	global_load_dwordx2 v[56:57], v[32:33], off
	global_load_dwordx2 v[54:55], v[32:33], off offset:512
	global_load_dwordx2 v[52:53], v[32:33], off offset:1024
	global_load_dwordx2 v[50:51], v[32:33], off offset:1536
	v_lshl_add_u64 v[32:33], v[36:37], 0, s[6:7]
	global_load_dwordx2 v[58:59], v[32:33], off offset:1536
	global_load_dwordx2 v[34:35], v[32:33], off offset:1024
	global_load_dwordx2 v[62:63], v[32:33], off offset:512
	s_nop 0
	global_load_dwordx2 v[32:33], v[32:33], off
	s_cmpk_gt_i32 s10, 0x7fff
	s_cselect_b64 s[10:11], -1, 0
	s_cbranch_vccnz .LBB0_517
; __device__ __forceinline__ void ln_phase(const float* XF, float* dst, bf16_t* XB, const float* g, const float* bt, const float* srcs, const float* PART, int npart, bool wf32, int gw, int ngw, int lane) {
;     ...
;             if (m >= MP) {
;                 const f32x4* sr = (const f32x4*)(srcs + (size_t)(m - MP) * DM) + lane;
; #pragma unroll
;                 for (int q = 0; q < 4; ++q) v[h][q] = sr[64 * q] * DN_ALPHA;
;                 for (int kc = 0; kc < npart; ++kc) { const f32x4* pr = (const f32x4*)(PART + ((size_t)kc * MS + (m - MP)) * DM) + lane;
; #pragma unroll
;                     for (int q = 0; q < 4; ++q) v[h][q] = v[h][q] + pr[64 * q]; }
	s_lshl_b64 s[6:7], s[90:91], 12
	s_waitcnt vmcnt(0)
	v_lshl_add_u64 v[108:109], v[38:39], 0, s[6:7]
	v_lshl_add_u64 v[110:111], v[40:41], 0, s[6:7]
	global_load_dwordx4 v[112:115], v[108:109], off
	global_load_dwordx4 v[116:119], v[108:109], off offset:1024
	global_load_dwordx4 v[120:123], v[108:109], off offset:2048
	global_load_dwordx4 v[124:127], v[108:109], off offset:3072
	global_load_dwordx4 v[198:201], v[110:111], off
	global_load_dwordx4 v[202:205], v[110:111], off offset:1024
	global_load_dwordx4 v[206:209], v[110:111], off offset:2048
	global_load_dwordx4 v[210:213], v[110:111], off offset:3072
	v_add_co_u32_e32 v140, vcc, 0x100000, v110
	s_nop 1
	v_addc_co_u32_e32 v141, vcc, 0, v111, vcc
	global_load_dwordx4 v[214:217], v[140:141], off
	global_load_dwordx4 v[218:221], v[140:141], off offset:1024
	global_load_dwordx4 v[222:225], v[140:141], off offset:2048
	global_load_dwordx4 v[226:229], v[140:141], off offset:3072
	v_add_co_u32_e32 v140, vcc, 0x200000, v110
	s_nop 1
	v_addc_co_u32_e32 v141, vcc, 0, v111, vcc
	global_load_dwordx4 v[230:233], v[140:141], off
	global_load_dwordx4 v[234:237], v[140:141], off offset:1024
	global_load_dwordx4 v[238:241], v[140:141], off offset:2048
	global_load_dwordx4 v[242:245], v[140:141], off offset:3072
	v_add_co_u32_e32 v140, vcc, 0x300000, v110
	s_nop 1
	v_addc_co_u32_e32 v141, vcc, 0, v111, vcc
	global_load_dwordx4 v[246:249], v[140:141], off
	global_load_dwordx4 v[128:131], v[140:141], off offset:1024
	global_load_dwordx4 v[132:135], v[140:141], off offset:2048
	global_load_dwordx4 v[136:139], v[140:141], off offset:3072
	s_waitcnt vmcnt(0)
	v_fma_f32 v66, v112, s92, v198
	v_fma_f32 v67, v113, s92, v199
	v_fma_f32 v32, v114, s92, v200
	v_fma_f32 v33, v115, s92, v201
	v_fma_f32 v60, v116, s92, v202
	v_fma_f32 v61, v117, s92, v203
	v_fma_f32 v62, v118, s92, v204
	v_fma_f32 v63, v119, s92, v205
	v_fma_f32 v58, v120, s92, v206
	v_fma_f32 v59, v121, s92, v207
	v_fma_f32 v34, v122, s92, v208
	v_fma_f32 v35, v123, s92, v209
	v_fma_f32 v64, v124, s92, v210
	v_fma_f32 v65, v125, s92, v211
	v_fma_f32 v70, v126, s92, v212
	v_fma_f32 v71, v127, s92, v213
	v_add_f32_e32 v66, v66, v214
	v_add_f32_e32 v67, v67, v215
	v_add_f32_e32 v32, v32, v216
	v_add_f32_e32 v33, v33, v217
	v_add_f32_e32 v60, v60, v218
	v_add_f32_e32 v61, v61, v219
	v_add_f32_e32 v62, v62, v220
	v_add_f32_e32 v63, v63, v221
	v_add_f32_e32 v58, v58, v222
	v_add_f32_e32 v59, v59, v223
	v_add_f32_e32 v34, v34, v224
	v_add_f32_e32 v35, v35, v225
	v_add_f32_e32 v64, v64, v226
	v_add_f32_e32 v65, v65, v227
	v_add_f32_e32 v70, v70, v228
	v_add_f32_e32 v71, v71, v229
	v_add_f32_e32 v66, v66, v230
	v_add_f32_e32 v67, v67, v231
	v_add_f32_e32 v32, v32, v232
	v_add_f32_e32 v33, v33, v233
	v_add_f32_e32 v60, v60, v234
	v_add_f32_e32 v61, v61, v235
	v_add_f32_e32 v62, v62, v236
	v_add_f32_e32 v63, v63, v237
	v_add_f32_e32 v58, v58, v238
	v_add_f32_e32 v59, v59, v239
	v_add_f32_e32 v34, v34, v240
	v_add_f32_e32 v35, v35, v241
	v_add_f32_e32 v64, v64, v242
	v_add_f32_e32 v65, v65, v243
	v_add_f32_e32 v70, v70, v244
	v_add_f32_e32 v71, v71, v245
	v_add_f32_e32 v66, v66, v246
	v_add_f32_e32 v67, v67, v247
	v_add_f32_e32 v32, v32, v248
	v_add_f32_e32 v33, v33, v249
	v_add_f32_e32 v60, v60, v128
	v_add_f32_e32 v61, v61, v129
	v_add_f32_e32 v62, v62, v130
	v_add_f32_e32 v63, v63, v131
	v_add_f32_e32 v58, v58, v132
	v_add_f32_e32 v59, v59, v133
	v_add_f32_e32 v34, v34, v134
	v_add_f32_e32 v35, v35, v135
	v_add_f32_e32 v64, v64, v136
	v_add_f32_e32 v65, v65, v137
	v_add_f32_e32 v70, v70, v138
	v_add_f32_e32 v71, v71, v139
	v_add_co_u32_e32 v140, vcc, 0x400000, v110
	s_nop 1
	v_addc_co_u32_e32 v141, vcc, 0, v111, vcc
	global_load_dwordx4 v[198:201], v[140:141], off
	global_load_dwordx4 v[202:205], v[140:141], off offset:1024
	global_load_dwordx4 v[206:209], v[140:141], off offset:2048
	global_load_dwordx4 v[210:213], v[140:141], off offset:3072
	v_add_co_u32_e32 v140, vcc, 0x500000, v110
	s_nop 1
	v_addc_co_u32_e32 v141, vcc, 0, v111, vcc
	global_load_dwordx4 v[214:217], v[140:141], off
	global_load_dwordx4 v[218:221], v[140:141], off offset:1024
	global_load_dwordx4 v[222:225], v[140:141], off offset:2048
	global_load_dwordx4 v[226:229], v[140:141], off offset:3072
	v_add_co_u32_e32 v140, vcc, 0x600000, v110
	s_nop 1
	v_addc_co_u32_e32 v141, vcc, 0, v111, vcc
	global_load_dwordx4 v[230:233], v[140:141], off
	global_load_dwordx4 v[234:237], v[140:141], off offset:1024
	global_load_dwordx4 v[238:241], v[140:141], off offset:2048
	global_load_dwordx4 v[242:245], v[140:141], off offset:3072
	v_add_co_u32_e32 v140, vcc, 0x700000, v110
	s_nop 1
	v_addc_co_u32_e32 v141, vcc, 0, v111, vcc
	global_load_dwordx4 v[246:249], v[140:141], off
	global_load_dwordx4 v[128:131], v[140:141], off offset:1024
	global_load_dwordx4 v[132:135], v[140:141], off offset:2048
	global_load_dwordx4 v[136:139], v[140:141], off offset:3072
	s_waitcnt vmcnt(0)
	v_add_f32_e32 v66, v66, v198
	v_add_f32_e32 v67, v67, v199
	v_add_f32_e32 v32, v32, v200
	v_add_f32_e32 v33, v33, v201
	v_add_f32_e32 v60, v60, v202
	v_add_f32_e32 v61, v61, v203
	v_add_f32_e32 v62, v62, v204
	v_add_f32_e32 v63, v63, v205
	v_add_f32_e32 v58, v58, v206
	v_add_f32_e32 v59, v59, v207
	v_add_f32_e32 v34, v34, v208
	v_add_f32_e32 v35, v35, v209
	v_add_f32_e32 v64, v64, v210
	v_add_f32_e32 v65, v65, v211
	v_add_f32_e32 v70, v70, v212
	v_add_f32_e32 v71, v71, v213
	v_add_f32_e32 v66, v66, v214
	v_add_f32_e32 v67, v67, v215
	v_add_f32_e32 v32, v32, v216
	v_add_f32_e32 v33, v33, v217
	v_add_f32_e32 v60, v60, v218
	v_add_f32_e32 v61, v61, v219
	v_add_f32_e32 v62, v62, v220
	v_add_f32_e32 v63, v63, v221
	v_add_f32_e32 v58, v58, v222
	v_add_f32_e32 v59, v59, v223
	v_add_f32_e32 v34, v34, v224
	v_add_f32_e32 v35, v35, v225
	v_add_f32_e32 v64, v64, v226
	v_add_f32_e32 v65, v65, v227
	v_add_f32_e32 v70, v70, v228
	v_add_f32_e32 v71, v71, v229
	v_add_f32_e32 v66, v66, v230
	v_add_f32_e32 v67, v67, v231
	v_add_f32_e32 v32, v32, v232
	v_add_f32_e32 v33, v33, v233
	v_add_f32_e32 v60, v60, v234
	v_add_f32_e32 v61, v61, v235
	v_add_f32_e32 v62, v62, v236
	v_add_f32_e32 v63, v63, v237
	v_add_f32_e32 v58, v58, v238
	v_add_f32_e32 v59, v59, v239
	v_add_f32_e32 v34, v34, v240
	v_add_f32_e32 v35, v35, v241
	v_add_f32_e32 v64, v64, v242
	v_add_f32_e32 v65, v65, v243
	v_add_f32_e32 v70, v70, v244
	v_add_f32_e32 v71, v71, v245
	v_add_f32_e32 v66, v66, v246
	v_add_f32_e32 v67, v67, v247
	v_add_f32_e32 v32, v32, v248
	v_add_f32_e32 v33, v33, v249
	v_add_f32_e32 v60, v60, v128
	v_add_f32_e32 v61, v61, v129
	v_add_f32_e32 v62, v62, v130
	v_add_f32_e32 v63, v63, v131
	v_add_f32_e32 v58, v58, v132
	v_add_f32_e32 v59, v59, v133
	v_add_f32_e32 v34, v34, v134
	v_add_f32_e32 v35, v35, v135
	v_add_f32_e32 v64, v64, v136
	v_add_f32_e32 v65, v65, v137
	v_add_f32_e32 v70, v70, v138
	v_add_f32_e32 v71, v71, v139
	s_branch .LBB0_518

; __device__ __forceinline__ void ln_phase(const float* XF, float* dst, bf16_t* XB, const float* g, const float* bt, const float* srcs, const float* PART, int npart, bool wf32, int gw, int ngw, int lane) {
;     ...
;     for (int m0 = gw; m0 < MT; m0 += 2 * ngw) {
;         f32x4 v[2][4];
; #pragma unroll
;         for (int h = 0; h < 2; ++h) {
;             const int m = m0 + h * ngw; const int mc = m < MT ? m : m0;
;             const u32x2* xr = (const u32x2*)((const bf16_t*)XF + (size_t)(mc < MP ? mc : 0) * DM) + lane;
; #pragma unroll
;             for (int q = 0; q < 4; ++q) { const u32x2 w = xr[64 * q]; v[h][q] = (f32x4){__uint_as_float(w.x << 16), __uint_as_float(w.x & 0xffff0000u), __uint_as_float(w.y << 16), __uint_as_float(w.y & 0xffff0000u)}; }
;         }
; #pragma unroll
;         for (int h = 0; h < 2; ++h) {
;             const int m = m0 + h * ngw;
;             if (m >= MT) continue;
;             if (m >= MP) {
;                 const f32x4* sr = (const f32x4*)(srcs + (size_t)(m - MP) * DM) + lane;
; #pragma unroll
;                 for (int q = 0; q < 4; ++q) v[h][q] = sr[64 * q] * DN_ALPHA;
;                 for (int kc = 0; kc < npart; ++kc) { const f32x4* pr = (const f32x4*)(PART + ((size_t)kc * MS + (m - MP)) * DM) + lane;
; #pragma unroll
;                     for (int q = 0; q < 4; ++q) v[h][q] = v[h][q] + pr[64 * q]; }
.LBB0_823:
	s_add_i32 s16, s66, s90
	s_add_i32 s18, s90, 0x8000
	s_add_i32 s17, s16, 0x8000
	s_cmp_lt_i32 s17, 0x8100
	s_cselect_b32 s4, s17, s18
	s_cmp_lt_i32 s4, 0x8000
	s_cselect_b32 s4, s4, 0
	s_ashr_i32 s5, s4, 31
	s_lshl_b64 s[4:5], s[4:5], 11
	s_cmp_lt_i32 s18, 0x8000
	v_lshl_add_u64 v[32:33], v[36:37], 0, s[4:5]
	s_cselect_b64 s[4:5], -1, 0
	s_and_b64 vcc, s[4:5], exec
	s_cselect_b32 s4, s18, 0
	s_ashr_i32 s5, s4, 31
	s_lshl_b64 s[4:5], s[4:5], 11
	global_load_dwordx2 v[50:51], v[32:33], off
	global_load_dwordx2 v[48:49], v[32:33], off offset:512
	global_load_dwordx2 v[46:47], v[32:33], off offset:1024
	global_load_dwordx2 v[44:45], v[32:33], off offset:1536
	v_lshl_add_u64 v[32:33], v[36:37], 0, s[4:5]
	global_load_dwordx2 v[34:35], v[32:33], off offset:1536
	global_load_dwordx2 v[54:55], v[32:33], off offset:1024
	global_load_dwordx2 v[56:57], v[32:33], off offset:512
	s_nop 0
	global_load_dwordx2 v[32:33], v[32:33], off
	s_cmpk_gt_i32 s18, 0x7fff
	s_cselect_b64 s[18:19], -1, 0
	s_cbranch_vccnz .LBB0_825
	s_lshl_b64 s[4:5], s[90:91], 12
	s_waitcnt vmcnt(0)
	v_lshl_add_u64 v[108:109], v[38:39], 0, s[4:5]
	v_lshl_add_u64 v[110:111], v[40:41], 0, s[4:5]
	global_load_dwordx4 v[112:115], v[108:109], off
	global_load_dwordx4 v[116:119], v[108:109], off offset:1024
	global_load_dwordx4 v[120:123], v[108:109], off offset:2048
	global_load_dwordx4 v[124:127], v[108:109], off offset:3072
	global_load_dwordx4 v[198:201], v[110:111], off
	global_load_dwordx4 v[202:205], v[110:111], off offset:1024
	global_load_dwordx4 v[206:209], v[110:111], off offset:2048
	global_load_dwordx4 v[210:213], v[110:111], off offset:3072
	v_add_co_u32_e32 v140, vcc, 0x100000, v110
	s_nop 1
	v_addc_co_u32_e32 v141, vcc, 0, v111, vcc
	global_load_dwordx4 v[214:217], v[140:141], off
	global_load_dwordx4 v[218:221], v[140:141], off offset:1024
	global_load_dwordx4 v[222:225], v[140:141], off offset:2048
	global_load_dwordx4 v[226:229], v[140:141], off offset:3072
	v_add_co_u32_e32 v140, vcc, 0x200000, v110
	s_nop 1
	v_addc_co_u32_e32 v141, vcc, 0, v111, vcc
	global_load_dwordx4 v[230:233], v[140:141], off
	global_load_dwordx4 v[234:237], v[140:141], off offset:1024
	global_load_dwordx4 v[238:241], v[140:141], off offset:2048
	global_load_dwordx4 v[242:245], v[140:141], off offset:3072
	v_add_co_u32_e32 v140, vcc, 0x300000, v110
	s_nop 1
	v_addc_co_u32_e32 v141, vcc, 0, v111, vcc
	global_load_dwordx4 v[246:249], v[140:141], off
	global_load_dwordx4 v[128:131], v[140:141], off offset:1024
	global_load_dwordx4 v[132:135], v[140:141], off offset:2048
	global_load_dwordx4 v[136:139], v[140:141], off offset:3072
	s_waitcnt vmcnt(0)
	v_fma_f32 v62, v112, s92, v198
	v_fma_f32 v63, v113, s92, v199
	v_fma_f32 v56, v114, s92, v200
	v_fma_f32 v57, v115, s92, v201
	v_fma_f32 v54, v116, s92, v202
	v_fma_f32 v55, v117, s92, v203
	v_fma_f32 v60, v118, s92, v204
	v_fma_f32 v61, v119, s92, v205
	v_fma_f32 v52, v120, s92, v206
	v_fma_f32 v53, v121, s92, v207
	v_fma_f32 v58, v122, s92, v208
	v_fma_f32 v59, v123, s92, v209
	v_fma_f32 v64, v124, s92, v210
	v_fma_f32 v65, v125, s92, v211
	v_fma_f32 v34, v126, s92, v212
	v_fma_f32 v35, v127, s92, v213
	v_add_f32_e32 v62, v62, v214
	v_add_f32_e32 v63, v63, v215
	v_add_f32_e32 v56, v56, v216
	v_add_f32_e32 v57, v57, v217
	v_add_f32_e32 v54, v54, v218
	v_add_f32_e32 v55, v55, v219
	v_add_f32_e32 v60, v60, v220
	v_add_f32_e32 v61, v61, v221
	v_add_f32_e32 v52, v52, v222
	v_add_f32_e32 v53, v53, v223
	v_add_f32_e32 v58, v58, v224
	v_add_f32_e32 v59, v59, v225
	v_add_f32_e32 v64, v64, v226
	v_add_f32_e32 v65, v65, v227
	v_add_f32_e32 v34, v34, v228
	v_add_f32_e32 v35, v35, v229
	v_add_f32_e32 v62, v62, v230
	v_add_f32_e32 v63, v63, v231
	v_add_f32_e32 v56, v56, v232
	v_add_f32_e32 v57, v57, v233
	v_add_f32_e32 v54, v54, v234
	v_add_f32_e32 v55, v55, v235
	v_add_f32_e32 v60, v60, v236
	v_add_f32_e32 v61, v61, v237
	v_add_f32_e32 v52, v52, v238
	v_add_f32_e32 v53, v53, v239
	v_add_f32_e32 v58, v58, v240
	v_add_f32_e32 v59, v59, v241
	v_add_f32_e32 v64, v64, v242
	v_add_f32_e32 v65, v65, v243
	v_add_f32_e32 v34, v34, v244
	v_add_f32_e32 v35, v35, v245
	v_add_f32_e32 v62, v62, v246
	v_add_f32_e32 v63, v63, v247
	v_add_f32_e32 v56, v56, v248
	v_add_f32_e32 v57, v57, v249
	v_add_f32_e32 v54, v54, v128
	v_add_f32_e32 v55, v55, v129
	v_add_f32_e32 v60, v60, v130
	v_add_f32_e32 v61, v61, v131
	v_add_f32_e32 v52, v52, v132
	v_add_f32_e32 v53, v53, v133
	v_add_f32_e32 v58, v58, v134
	v_add_f32_e32 v59, v59, v135
	v_add_f32_e32 v64, v64, v136
	v_add_f32_e32 v65, v65, v137
	v_add_f32_e32 v34, v34, v138
	v_add_f32_e32 v35, v35, v139
	v_add_co_u32_e32 v140, vcc, 0x400000, v110
	s_nop 1
	v_addc_co_u32_e32 v141, vcc, 0, v111, vcc
	global_load_dwordx4 v[198:201], v[140:141], off
	global_load_dwordx4 v[202:205], v[140:141], off offset:1024
	global_load_dwordx4 v[206:209], v[140:141], off offset:2048
	global_load_dwordx4 v[210:213], v[140:141], off offset:3072
	v_add_co_u32_e32 v140, vcc, 0x500000, v110
	s_nop 1
	v_addc_co_u32_e32 v141, vcc, 0, v111, vcc
	global_load_dwordx4 v[214:217], v[140:141], off
	global_load_dwordx4 v[218:221], v[140:141], off offset:1024
	global_load_dwordx4 v[222:225], v[140:141], off offset:2048
	global_load_dwordx4 v[226:229], v[140:141], off offset:3072
	v_add_co_u32_e32 v140, vcc, 0x600000, v110
	s_nop 1
	v_addc_co_u32_e32 v141, vcc, 0, v111, vcc
	global_load_dwordx4 v[230:233], v[140:141], off
	global_load_dwordx4 v[234:237], v[140:141], off offset:1024
	global_load_dwordx4 v[238:241], v[140:141], off offset:2048
	global_load_dwordx4 v[242:245], v[140:141], off offset:3072
	v_add_co_u32_e32 v140, vcc, 0x700000, v110
	s_nop 1
	v_addc_co_u32_e32 v141, vcc, 0, v111, vcc
	global_load_dwordx4 v[246:249], v[140:141], off
	global_load_dwordx4 v[128:131], v[140:141], off offset:1024
	global_load_dwordx4 v[132:135], v[140:141], off offset:2048
	global_load_dwordx4 v[136:139], v[140:141], off offset:3072
	s_waitcnt vmcnt(0)
; __device__ __forceinline__ void ln_phase(const float* XF, float* dst, bf16_t* XB, const float* g, const float* bt, const float* srcs, const float* PART, int npart, bool wf32, int gw, int ngw, int lane) {
;     ...
;                 for (int kc = 0; kc < npart; ++kc) { const f32x4* pr = (const f32x4*)(PART + ((size_t)kc * MS + (m - MP)) * DM) + lane;
; #pragma unroll
;                     for (int q = 0; q < 4; ++q) v[h][q] = v[h][q] + pr[64 * q]; }
	v_add_f32_e32 v62, v62, v198
	v_add_f32_e32 v63, v63, v199
	v_add_f32_e32 v56, v56, v200
	v_add_f32_e32 v57, v57, v201
	v_add_f32_e32 v54, v54, v202
	v_add_f32_e32 v55, v55, v203
	v_add_f32_e32 v60, v60, v204
	v_add_f32_e32 v61, v61, v205
	v_add_f32_e32 v52, v52, v206
	v_add_f32_e32 v53, v53, v207
	v_add_f32_e32 v58, v58, v208
	v_add_f32_e32 v59, v59, v209
	v_add_f32_e32 v64, v64, v210
	v_add_f32_e32 v65, v65, v211
	v_add_f32_e32 v34, v34, v212
	v_add_f32_e32 v35, v35, v213
	v_add_f32_e32 v62, v62, v214
	v_add_f32_e32 v63, v63, v215
	v_add_f32_e32 v56, v56, v216
	v_add_f32_e32 v57, v57, v217
	v_add_f32_e32 v54, v54, v218
	v_add_f32_e32 v55, v55, v219
	v_add_f32_e32 v60, v60, v220
	v_add_f32_e32 v61, v61, v221
	v_add_f32_e32 v52, v52, v222
	v_add_f32_e32 v53, v53, v223
	v_add_f32_e32 v58, v58, v224
	v_add_f32_e32 v59, v59, v225
	v_add_f32_e32 v64, v64, v226
	v_add_f32_e32 v65, v65, v227
	v_add_f32_e32 v34, v34, v228
	v_add_f32_e32 v35, v35, v229
	v_add_f32_e32 v62, v62, v230
	v_add_f32_e32 v63, v63, v231
	v_add_f32_e32 v56, v56, v232
	v_add_f32_e32 v57, v57, v233
	v_add_f32_e32 v54, v54, v234
	v_add_f32_e32 v55, v55, v235
	v_add_f32_e32 v60, v60, v236
	v_add_f32_e32 v61, v61, v237
	v_add_f32_e32 v52, v52, v238
	v_add_f32_e32 v53, v53, v239
	v_add_f32_e32 v58, v58, v240
	v_add_f32_e32 v59, v59, v241
	v_add_f32_e32 v64, v64, v242
	v_add_f32_e32 v65, v65, v243
	v_add_f32_e32 v34, v34, v244
	v_add_f32_e32 v35, v35, v245
	v_add_f32_e32 v62, v62, v246
	v_add_f32_e32 v63, v63, v247
	v_add_f32_e32 v56, v56, v248
	v_add_f32_e32 v57, v57, v249
	v_add_f32_e32 v54, v54, v128
	v_add_f32_e32 v55, v55, v129
	v_add_f32_e32 v60, v60, v130
	v_add_f32_e32 v61, v61, v131
	v_add_f32_e32 v52, v52, v132
	v_add_f32_e32 v53, v53, v133
	v_add_f32_e32 v58, v58, v134
	v_add_f32_e32 v59, v59, v135
	v_add_f32_e32 v64, v64, v136
	v_add_f32_e32 v65, v65, v137
	v_add_f32_e32 v34, v34, v138
	v_add_f32_e32 v35, v35, v139
	v_add_co_u32_e32 v140, vcc, 0x800000, v110
	s_nop 1
	v_addc_co_u32_e32 v141, vcc, 0, v111, vcc
	global_load_dwordx4 v[198:201], v[140:141], off
	global_load_dwordx4 v[202:205], v[140:141], off offset:1024
	global_load_dwordx4 v[206:209], v[140:141], off offset:2048
	global_load_dwordx4 v[210:213], v[140:141], off offset:3072
	v_add_co_u32_e32 v140, vcc, 0x900000, v110
	s_nop 1
	v_addc_co_u32_e32 v141, vcc, 0, v111, vcc
	global_load_dwordx4 v[214:217], v[140:141], off
	global_load_dwordx4 v[218:221], v[140:141], off offset:1024
	global_load_dwordx4 v[222:225], v[140:141], off offset:2048
	global_load_dwordx4 v[226:229], v[140:141], off offset:3072
	v_add_co_u32_e32 v140, vcc, 0xa00000, v110
	s_nop 1
	v_addc_co_u32_e32 v141, vcc, 0, v111, vcc
	global_load_dwordx4 v[230:233], v[140:141], off
	global_load_dwordx4 v[234:237], v[140:141], off offset:1024
	global_load_dwordx4 v[238:241], v[140:141], off offset:2048
	global_load_dwordx4 v[242:245], v[140:141], off offset:3072
	v_add_co_u32_e32 v140, vcc, 0xb00000, v110
	s_nop 1
	v_addc_co_u32_e32 v141, vcc, 0, v111, vcc
	global_load_dwordx4 v[246:249], v[140:141], off
	global_load_dwordx4 v[128:131], v[140:141], off offset:1024
	global_load_dwordx4 v[132:135], v[140:141], off offset:2048
	global_load_dwordx4 v[136:139], v[140:141], off offset:3072
	s_waitcnt vmcnt(0)
; __device__ __forceinline__ void ln_phase(const float* XF, float* dst, bf16_t* XB, const float* g, const float* bt, const float* srcs, const float* PART, int npart, bool wf32, int gw, int ngw, int lane) {
;     ...
;                 for (int kc = 0; kc < npart; ++kc) { const f32x4* pr = (const f32x4*)(PART + ((size_t)kc * MS + (m - MP)) * DM) + lane;
; #pragma unroll
;                     for (int q = 0; q < 4; ++q) v[h][q] = v[h][q] + pr[64 * q]; }
	v_add_f32_e32 v62, v62, v198
	v_add_f32_e32 v63, v63, v199
	v_add_f32_e32 v56, v56, v200
	v_add_f32_e32 v57, v57, v201
	v_add_f32_e32 v54, v54, v202
	v_add_f32_e32 v55, v55, v203
	v_add_f32_e32 v60, v60, v204
	v_add_f32_e32 v61, v61, v205
	v_add_f32_e32 v52, v52, v206
	v_add_f32_e32 v53, v53, v207
	v_add_f32_e32 v58, v58, v208
	v_add_f32_e32 v59, v59, v209
	v_add_f32_e32 v64, v64, v210
	v_add_f32_e32 v65, v65, v211
	v_add_f32_e32 v34, v34, v212
	v_add_f32_e32 v35, v35, v213
	v_add_f32_e32 v62, v62, v214
	v_add_f32_e32 v63, v63, v215
	v_add_f32_e32 v56, v56, v216
	v_add_f32_e32 v57, v57, v217
	v_add_f32_e32 v54, v54, v218
	v_add_f32_e32 v55, v55, v219
	v_add_f32_e32 v60, v60, v220
	v_add_f32_e32 v61, v61, v221
	v_add_f32_e32 v52, v52, v222
	v_add_f32_e32 v53, v53, v223
	v_add_f32_e32 v58, v58, v224
	v_add_f32_e32 v59, v59, v225
	v_add_f32_e32 v64, v64, v226
	v_add_f32_e32 v65, v65, v227
	v_add_f32_e32 v34, v34, v228
	v_add_f32_e32 v35, v35, v229
	v_add_f32_e32 v62, v62, v230
	v_add_f32_e32 v63, v63, v231
	v_add_f32_e32 v56, v56, v232
	v_add_f32_e32 v57, v57, v233
	v_add_f32_e32 v54, v54, v234
	v_add_f32_e32 v55, v55, v235
	v_add_f32_e32 v60, v60, v236
	v_add_f32_e32 v61, v61, v237
	v_add_f32_e32 v52, v52, v238
	v_add_f32_e32 v53, v53, v239
	v_add_f32_e32 v58, v58, v240
	v_add_f32_e32 v59, v59, v241
	v_add_f32_e32 v64, v64, v242
	v_add_f32_e32 v65, v65, v243
	v_add_f32_e32 v34, v34, v244
	v_add_f32_e32 v35, v35, v245
	v_add_f32_e32 v62, v62, v246
	v_add_f32_e32 v63, v63, v247
	v_add_f32_e32 v56, v56, v248
	v_add_f32_e32 v57, v57, v249
	v_add_f32_e32 v54, v54, v128
	v_add_f32_e32 v55, v55, v129
	v_add_f32_e32 v60, v60, v130
	v_add_f32_e32 v61, v61, v131
	v_add_f32_e32 v52, v52, v132
	v_add_f32_e32 v53, v53, v133
	v_add_f32_e32 v58, v58, v134
	v_add_f32_e32 v59, v59, v135
	v_add_f32_e32 v64, v64, v136
	v_add_f32_e32 v65, v65, v137
	v_add_f32_e32 v34, v34, v138
	v_add_f32_e32 v35, v35, v139
	v_add_co_u32_e32 v140, vcc, 0xc00000, v110
	s_nop 1
	v_addc_co_u32_e32 v141, vcc, 0, v111, vcc
	global_load_dwordx4 v[198:201], v[140:141], off
	global_load_dwordx4 v[202:205], v[140:141], off offset:1024
	global_load_dwordx4 v[206:209], v[140:141], off offset:2048
	global_load_dwordx4 v[210:213], v[140:141], off offset:3072
	v_add_co_u32_e32 v140, vcc, 0xd00000, v110
	s_nop 1
	v_addc_co_u32_e32 v141, vcc, 0, v111, vcc
	global_load_dwordx4 v[214:217], v[140:141], off
	global_load_dwordx4 v[218:221], v[140:141], off offset:1024
	global_load_dwordx4 v[222:225], v[140:141], off offset:2048
	global_load_dwordx4 v[226:229], v[140:141], off offset:3072
	v_add_co_u32_e32 v140, vcc, 0xe00000, v110
	s_nop 1
	v_addc_co_u32_e32 v141, vcc, 0, v111, vcc
	global_load_dwordx4 v[230:233], v[140:141], off
	global_load_dwordx4 v[234:237], v[140:141], off offset:1024
	global_load_dwordx4 v[238:241], v[140:141], off offset:2048
	global_load_dwordx4 v[242:245], v[140:141], off offset:3072
	v_add_co_u32_e32 v140, vcc, 0xf00000, v110
	s_nop 1
	v_addc_co_u32_e32 v141, vcc, 0, v111, vcc
	global_load_dwordx4 v[246:249], v[140:141], off
	global_load_dwordx4 v[128:131], v[140:141], off offset:1024
	global_load_dwordx4 v[132:135], v[140:141], off offset:2048
	global_load_dwordx4 v[136:139], v[140:141], off offset:3072
	s_waitcnt vmcnt(0)
	v_add_f32_e32 v62, v62, v198
	v_add_f32_e32 v63, v63, v199
	v_add_f32_e32 v56, v56, v200
	v_add_f32_e32 v57, v57, v201
	v_add_f32_e32 v54, v54, v202
	v_add_f32_e32 v55, v55, v203
	v_add_f32_e32 v60, v60, v204
	v_add_f32_e32 v61, v61, v205
	v_add_f32_e32 v52, v52, v206
	v_add_f32_e32 v53, v53, v207
	v_add_f32_e32 v58, v58, v208
	v_add_f32_e32 v59, v59, v209
	v_add_f32_e32 v64, v64, v210
	v_add_f32_e32 v65, v65, v211
	v_add_f32_e32 v34, v34, v212
	v_add_f32_e32 v35, v35, v213
	v_add_f32_e32 v62, v62, v214
	v_add_f32_e32 v63, v63, v215
	v_add_f32_e32 v56, v56, v216
	v_add_f32_e32 v57, v57, v217
	v_add_f32_e32 v54, v54, v218
	v_add_f32_e32 v55, v55, v219
	v_add_f32_e32 v60, v60, v220
	v_add_f32_e32 v61, v61, v221
	v_add_f32_e32 v52, v52, v222
	v_add_f32_e32 v53, v53, v223
	v_add_f32_e32 v58, v58, v224
	v_add_f32_e32 v59, v59, v225
	v_add_f32_e32 v64, v64, v226
	v_add_f32_e32 v65, v65, v227
	v_add_f32_e32 v34, v34, v228
	v_add_f32_e32 v35, v35, v229
	v_add_f32_e32 v62, v62, v230
	v_add_f32_e32 v63, v63, v231
	v_add_f32_e32 v56, v56, v232
	v_add_f32_e32 v57, v57, v233
	v_add_f32_e32 v54, v54, v234
	v_add_f32_e32 v55, v55, v235
	v_add_f32_e32 v60, v60, v236
	v_add_f32_e32 v61, v61, v237
	v_add_f32_e32 v52, v52, v238
	v_add_f32_e32 v53, v53, v239
	v_add_f32_e32 v58, v58, v240
	v_add_f32_e32 v59, v59, v241
	v_add_f32_e32 v64, v64, v242
	v_add_f32_e32 v65, v65, v243
	v_add_f32_e32 v34, v34, v244
	v_add_f32_e32 v35, v35, v245
	v_add_f32_e32 v62, v62, v246
	v_add_f32_e32 v63, v63, v247
	v_add_f32_e32 v56, v56, v248
	v_add_f32_e32 v57, v57, v249
	v_add_f32_e32 v54, v54, v128
	v_add_f32_e32 v55, v55, v129
	v_add_f32_e32 v60, v60, v130
	v_add_f32_e32 v61, v61, v131
	v_add_f32_e32 v52, v52, v132
	v_add_f32_e32 v53, v53, v133
	v_add_f32_e32 v58, v58, v134
	v_add_f32_e32 v59, v59, v135
	v_add_f32_e32 v64, v64, v136
	v_add_f32_e32 v65, v65, v137
	v_add_f32_e32 v34, v34, v138
	v_add_f32_e32 v35, v35, v139
	s_branch .LBB0_826
